# attention QK double-buffer + PV 6-deep V-fragment prefetch; row-sum chain uses scalar v_add_f32 pairs instead of v_pk_add_f32 beside the PV MFMAs (bit-identical arithmetic)
# baseline (speedup 1.0000x reference)
; __device__ __forceinline__ unsigned cvtpk(float lo, float hi) { return pg8::cvt_pk_bf16(lo, hi); }
; __device__ __forceinline__ void attn_phase(LAS unsigned char* lds, const bf16_t* proj, bf16_t* oa, const float* lamp, const float* subg, const float* relb, const float* qg, int wg, int tid) {
;     ...
;                 for (int s = 0; s < 2; ++s) { float ps = 0.f;
; #pragma unroll
;                     for (int T = 0; T < 2; ++T)
; #pragma unroll
;                         for (int r = 0; r < 4; ++r) { const float p = __builtin_amdgcn_exp2f(st[s][T][r]); st[s][T][r] = p; ps += p; }
;                     if (s == 0) l0 += ps; else l1 += ps;
;                     u32x4 w; w.x = cvtpk(st[s][0][0], st[s][0][1]); w.y = cvtpk(st[s][0][2], st[s][0][3]); w.z = cvtpk(st[s][1][0], st[s][1][1]); w.w = cvtpk(st[s][1][2], st[s][1][3]);
;                     pf[s] = __builtin_bit_cast(bf16x8, w); }
.LBB0_633:
	s_mul_i32 s30, s46, 0x4400
	v_add_u32_e32 v0, s30, v246
	v_exp_f32_e32 v231, v146
	v_exp_f32_e32 v229, v147
	v_exp_f32_e32 v227, v148
	v_exp_f32_e32 v225, v149
	v_exp_f32_e32 v223, v150
	v_exp_f32_e32 v221, v151
	v_exp_f32_e32 v165, v152
	v_exp_f32_e32 v163, v153
	v_exp_f32_e32 v230, v158
	v_exp_f32_e32 v228, v159
	v_exp_f32_e32 v226, v160
	v_exp_f32_e32 v224, v161
	v_exp_f32_e32 v222, v154
	v_exp_f32_e32 v220, v155
	v_exp_f32_e32 v164, v156
	v_exp_f32_e32 v162, v157
	ds_read_b64_tr_b16 v[158:159], v0 offset:36864
	ds_read_b64_tr_b16 v[160:161], v0 offset:45568
	ds_read_b64_tr_b16 v[154:155], v0 offset:36896
	ds_read_b64_tr_b16 v[156:157], v0 offset:45600
	v_cvt_pk_bf16_f32 v146, v231, v229
	v_cvt_pk_bf16_f32 v147, v227, v225
	v_cvt_pk_bf16_f32 v148, v223, v221
	v_cvt_pk_bf16_f32 v149, v165, v163
	v_cvt_pk_bf16_f32 v150, v230, v228
	v_cvt_pk_bf16_f32 v151, v226, v224
	v_cvt_pk_bf16_f32 v152, v222, v220
	v_cvt_pk_bf16_f32 v153, v164, v162
	v_add_f32_e64 v230, v230, 0
	v_add_f32_e64 v231, v231, 0
	v_add_f32_e32 v228, v228, v230
	v_add_f32_e32 v229, v229, v231
	v_add_f32_e32 v226, v226, v228
	v_add_f32_e32 v227, v227, v229
	v_add_f32_e64 v226, v224, v226
	v_add_f32_e64 v227, v225, v227
	v_add_f32_e32 v226, v222, v226
	v_add_f32_e32 v227, v223, v227
	v_add_f32_e64 v226, v220, v226
	v_add_f32_e64 v227, v221, v227
	v_add_f32_e32 v226, v164, v226
	v_add_f32_e32 v227, v165, v227
	v_add_f32_e64 v226, v162, v226
	v_add_f32_e64 v227, v163, v227
	v_add_f32_e32 v218, v218, v226
	v_add_f32_e32 v219, v219, v227
	ds_read_b64_tr_b16 v[162:163], v0 offset:36928
	ds_read_b64_tr_b16 v[164:165], v0 offset:45632
	ds_read_b64_tr_b16 v[220:221], v0 offset:36960
	ds_read_b64_tr_b16 v[222:223], v0 offset:45664
	ds_read_b64_tr_b16 v[224:225], v0 offset:36992
	ds_read_b64_tr_b16 v[226:227], v0 offset:45696
	ds_read_b64_tr_b16 v[228:229], v0 offset:37024
	ds_read_b64_tr_b16 v[230:231], v0 offset:45728
	s_waitcnt lgkmcnt(10)
	v_mfma_f32_16x16x32_bf16 v[142:145], v[158:161], v[146:149], v[142:145]
	v_mfma_f32_16x16x32_bf16 v[138:141], v[158:161], v[150:153], v[138:141]
	ds_read_b64_tr_b16 v[158:159], v0 offset:37056
	ds_read_b64_tr_b16 v[160:161], v0 offset:45760
	s_waitcnt lgkmcnt(10)
	v_mfma_f32_16x16x32_bf16 v[134:137], v[154:157], v[146:149], v[134:137]
	v_mfma_f32_16x16x32_bf16 v[130:133], v[154:157], v[150:153], v[130:133]
	ds_read_b64_tr_b16 v[154:155], v0 offset:37088
	ds_read_b64_tr_b16 v[156:157], v0 offset:45792
	s_waitcnt lgkmcnt(10)
	v_mfma_f32_16x16x32_bf16 v[126:129], v[162:165], v[146:149], v[126:129]
	v_mfma_f32_16x16x32_bf16 v[122:125], v[162:165], v[150:153], v[122:125]
	ds_read_b64_tr_b16 v[162:163], v0 offset:37120
	ds_read_b64_tr_b16 v[164:165], v0 offset:45824
	s_waitcnt lgkmcnt(10)
	v_mfma_f32_16x16x32_bf16 v[118:121], v[220:223], v[146:149], v[118:121]
	v_mfma_f32_16x16x32_bf16 v[114:117], v[220:223], v[150:153], v[114:117]
	ds_read_b64_tr_b16 v[220:221], v0 offset:37152
	ds_read_b64_tr_b16 v[222:223], v0 offset:45856
	s_waitcnt lgkmcnt(10)
	v_mfma_f32_16x16x32_bf16 v[110:113], v[224:227], v[146:149], v[110:113]
	v_mfma_f32_16x16x32_bf16 v[106:109], v[224:227], v[150:153], v[106:109]
	ds_read_b64_tr_b16 v[224:225], v0 offset:37184
	ds_read_b64_tr_b16 v[226:227], v0 offset:45888
	s_waitcnt lgkmcnt(10)
	v_mfma_f32_16x16x32_bf16 v[102:105], v[228:231], v[146:149], v[102:105]
	v_mfma_f32_16x16x32_bf16 v[98:101], v[228:231], v[150:153], v[98:101]
	ds_read_b64_tr_b16 v[228:229], v0 offset:37216
	ds_read_b64_tr_b16 v[230:231], v0 offset:45920
	s_waitcnt lgkmcnt(10)
	v_mfma_f32_16x16x32_bf16 v[94:97], v[158:161], v[146:149], v[94:97]
	v_mfma_f32_16x16x32_bf16 v[90:93], v[158:161], v[150:153], v[90:93]
	ds_read_b64_tr_b16 v[158:159], v0 offset:37248
	ds_read_b64_tr_b16 v[160:161], v0 offset:45952
	s_waitcnt lgkmcnt(10)
	v_mfma_f32_16x16x32_bf16 v[86:89], v[154:157], v[146:149], v[86:89]
	v_mfma_f32_16x16x32_bf16 v[82:85], v[154:157], v[150:153], v[82:85]
	ds_read_b64_tr_b16 v[154:155], v0 offset:37280
	ds_read_b64_tr_b16 v[156:157], v0 offset:45984
	s_waitcnt lgkmcnt(10)
	v_mfma_f32_16x16x32_bf16 v[78:81], v[162:165], v[146:149], v[78:81]
	v_mfma_f32_16x16x32_bf16 v[74:77], v[162:165], v[150:153], v[74:77]
	ds_read_b64_tr_b16 v[162:163], v0 offset:37312
	ds_read_b64_tr_b16 v[164:165], v0 offset:46016
	s_waitcnt lgkmcnt(10)
	v_mfma_f32_16x16x32_bf16 v[70:73], v[220:223], v[146:149], v[70:73]
	v_mfma_f32_16x16x32_bf16 v[66:69], v[220:223], v[150:153], v[66:69]
	ds_read_b64_tr_b16 v[220:221], v0 offset:37344
	ds_read_b64_tr_b16 v[222:223], v0 offset:46048
	s_waitcnt lgkmcnt(10)
	v_mfma_f32_16x16x32_bf16 v[62:65], v[224:227], v[146:149], v[62:65]
	v_mfma_f32_16x16x32_bf16 v[58:61], v[224:227], v[150:153], v[58:61]
	s_waitcnt lgkmcnt(8)
	v_mfma_f32_16x16x32_bf16 v[54:57], v[228:231], v[146:149], v[54:57]
	v_mfma_f32_16x16x32_bf16 v[50:53], v[228:231], v[150:153], v[50:53]
	s_waitcnt lgkmcnt(6)
	v_mfma_f32_16x16x32_bf16 v[46:49], v[158:161], v[146:149], v[46:49]
	v_mfma_f32_16x16x32_bf16 v[42:45], v[158:161], v[150:153], v[42:45]
	s_waitcnt lgkmcnt(4)
	v_mfma_f32_16x16x32_bf16 v[38:41], v[154:157], v[146:149], v[38:41]
	v_mfma_f32_16x16x32_bf16 v[30:33], v[154:157], v[150:153], v[30:33]
	s_waitcnt lgkmcnt(2)
	v_mfma_f32_16x16x32_bf16 v[34:37], v[162:165], v[146:149], v[34:37]
	v_mfma_f32_16x16x32_bf16 v[22:25], v[162:165], v[150:153], v[22:25]
	s_waitcnt lgkmcnt(0)
	v_mfma_f32_16x16x32_bf16 v[26:29], v[220:223], v[146:149], v[26:29]
	v_mfma_f32_16x16x32_bf16 v[18:21], v[220:223], v[150:153], v[18:21]
	s_andn2_b64 vcc, exec, s[20:21]
	s_cbranch_vccnz .LBB0_594
